# v069 + counted waits in the GEMM prologues: vmcnt(7) instead of a full drain before the 8th LDS-DMA load (out-proj, FFN-out), stale drain removed (in-proj)
# baseline (speedup 1.0000x reference)
.LBB0_224:
	s_and_b64 vcc, exec, s[10:11]
	s_mul_i32 s94, s5, 0x1800000
	s_cbranch_vccnz .LBB0_348
	v_ashrrev_i32_e32 v2, 31, v12
	v_lshrrev_b32_e32 v2, 26, v2
	v_add_u32_e32 v2, v12, v2
	v_ashrrev_i32_e32 v13, 6, v2
	v_bfe_i32 v2, v12, 27, 1
	v_lshlrev_b32_e32 v4, 4, v12
	v_lshrrev_b32_e32 v2, 22, v2
	v_add_u32_e32 v2, v4, v2
	v_and_b32_e32 v2, 0xfffffc00, v2
	v_sub_u32_e32 v2, v4, v2
	v_lshrrev_b32_e32 v5, 4, v2
	v_bitop3_b32 v2, v5, v2, 32 bitop3:0x6c
	v_ashrrev_i32_e32 v6, 31, v2
	v_lshrrev_b32_e32 v6, 26, v6
	v_add_u32_e32 v6, v2, v6
	v_lshlrev_b32_e32 v5, 3, v13
	v_ashrrev_i32_e32 v14, 6, v6
	v_and_b32_e32 v6, 0xc0, v6
	v_and_b32_e32 v5, -16, v5
	v_sub_u32_e32 v2, v2, v6
	v_add_u32_e32 v5, v14, v5
	v_ashrrev_i16_sdwa v2, v195, sext(v2) dst_sel:DWORD dst_unused:UNUSED_PAD src0_sel:DWORD src1_sel:BYTE_0
	v_lshlrev_b32_e32 v7, 5, v13
	v_bfe_i32 v15, v2, 0, 16
	v_lshlrev_b32_e32 v2, 1, v5
	v_lshrrev_b32_e32 v6, 2, v5
	v_and_b32_e32 v8, 3, v14
	s_mov_b32 s4, 0x1fffe0
	v_and_b32_e32 v7, 32, v7
	v_and_b32_e32 v2, 24, v2
	v_and_b32_e32 v6, 4, v6
	v_and_or_b32 v8, v5, s4, v8
	v_or3_b32 v2, v8, v6, v2
	v_add_lshl_u32 v6, v7, v15, 1
	v_add_u32_e32 v4, 0x2000, v4
	v_lshl_add_u32 v148, v5, 11, v6
	v_ashrrev_i32_e32 v5, 31, v4
	v_lshrrev_b32_e32 v5, 22, v5
	v_add_u32_e32 v5, v4, v5
	v_ashrrev_i32_e32 v16, 10, v5
	v_mul_i32_i24_e32 v5, 0x400, v16
	v_sub_u32_e32 v4, v4, v5
	v_lshrrev_b32_e32 v5, 4, v4
	v_bitop3_b32 v4, v5, v4, 32 bitop3:0x6c
	v_lshl_add_u32 v2, v2, 11, v6
	v_ashrrev_i32_e32 v6, 31, v4
	v_lshrrev_b32_e32 v6, 26, v6
	v_lshlrev_b32_e32 v5, 3, v16
	v_add_u32_e32 v6, v4, v6
	s_ashr_i32 s10, s6, 6
	v_and_b32_e32 v5, -16, v5
	v_ashrrev_i32_e32 v17, 6, v6
	v_add_u32_e32 v5, v17, v5
	v_and_b32_e32 v8, 3, v17
	s_ashr_i32 s24, s6, 8
	s_lshl_b32 s57, s10, 10
	v_and_or_b32 v8, v5, s4, v8
	s_add_u32 s4, s12, s94
	s_addc_u32 s9, s13, 0
	s_add_u32 s83, s4, 0x400000
	s_addc_u32 s97, s9, 0
	s_add_u32 s84, s12, 0x3400000
	v_and_b32_e32 v6, 0xc0, v6
	s_addc_u32 s34, s13, 0
	s_ashr_i32 s17, s16, 31
	s_ashr_i32 s15, s14, 31
	v_sub_u32_e32 v4, v4, v6
	s_lshl_b64 s[18:19], s[16:17], 19
	s_lshl_b64 s[20:21], s[14:15], 19
	v_ashrrev_i16_sdwa v4, v195, sext(v4) dst_sel:DWORD dst_unused:UNUSED_PAD src0_sel:DWORD src1_sel:BYTE_0
	s_add_u32 s76, s83, s20
	v_lshlrev_b32_e32 v7, 5, v16
	v_bfe_i32 v18, v4, 0, 16
	v_lshlrev_b32_e32 v4, 1, v5
	v_lshrrev_b32_e32 v6, 2, v5
	s_addc_u32 s77, s97, s21
	s_add_i32 s35, s57, 0
	v_and_b32_e32 v7, 32, v7
	v_and_b32_e32 v4, 24, v4
	v_and_b32_e32 v6, 4, v6
	s_add_i32 m0, s35, 0x10000
	v_or3_b32 v4, v8, v6, v4
	v_add_lshl_u32 v6, v7, v18, 1
	global_load_lds_dwordx4 v2, s[76:77]
	s_add_i32 m0, s35, 0x12000
	v_lshl_add_u32 v152, v4, 11, v6
	s_add_u32 s20, s76, 0x40000
	global_load_lds_dwordx4 v152, s[76:77]
	s_addc_u32 s21, s77, 0
	s_add_i32 m0, s35, 0x14000
	v_lshl_add_u32 v150, v5, 11, v6
	global_load_lds_dwordx4 v2, s[20:21]
	s_add_i32 m0, s35, 0x16000
	s_add_u32 s18, s84, s18
	s_addc_u32 s19, s34, s19
	s_add_i32 s9, s35, 0x2000
	global_load_lds_dwordx4 v152, s[20:21]
	s_mov_b32 m0, s35
	s_add_u32 s58, s18, 0x40000
	global_load_lds_dwordx4 v148, s[18:19]
	s_mov_b32 m0, s9
	s_addc_u32 s59, s19, 0
	s_add_i32 s4, s35, 0x4000
	global_load_lds_dwordx4 v150, s[18:19]
	s_mov_b32 m0, s4
	s_add_i32 s20, s35, 0x6000
	global_load_lds_dwordx4 v148, s[58:59]
	s_mov_b32 m0, s20
	v_mov_b32_e32 v153, v3
	global_load_lds_dwordx4 v150, s[58:59]
	v_mov_b32_e32 v149, v3
	v_mov_b32_e32 v151, v3
	s_cmp_eq_u32 s24, 1
	v_lshl_add_u64 v[10:11], s[76:77], 0, v[2:3]
	v_lshl_add_u64 v[8:9], s[76:77], 0, v[152:153]
	v_lshl_add_u64 v[4:5], s[18:19], 0, v[148:149]
	s_cselect_b64 s[58:59], -1, 0
	s_cmp_lg_u32 s24, 1
	v_lshl_add_u64 v[6:7], s[18:19], 0, v[150:151]
	s_cbranch_scc1 .LBB0_227
	s_barrier

.LBB0_593:
	s_or_b64 exec, exec, s[60:61]
	v_ashrrev_i32_e32 v2, 31, v154
	v_lshrrev_b32_e32 v2, 26, v2
	v_add_u32_e32 v2, v154, v2
	v_ashrrev_i32_e32 v139, 6, v2
	v_bfe_i32 v2, v154, 27, 1
	v_lshlrev_b32_e32 v133, 4, v154
	v_lshrrev_b32_e32 v2, 22, v2
	v_add_u32_e32 v2, v133, v2
	v_and_b32_e32 v2, 0xfffffc00, v2
	v_sub_u32_e32 v2, v133, v2
	v_lshrrev_b32_e32 v132, 4, v2
	v_bitop3_b32 v2, v132, v2, 32 bitop3:0x6c
	v_ashrrev_i32_e32 v134, 31, v2
	s_lshr_b32 s6, s6, 3
	v_lshrrev_b32_e32 v134, 26, v134
	s_add_u32 s11, s16, s94
	v_add_u32_e32 v134, v2, v134
	s_addc_u32 s12, s17, 0
	v_lshlrev_b32_e32 v132, 3, v139
	v_ashrrev_i32_e32 v140, 6, v134
	v_and_b32_e32 v134, 0xc0, v134
	s_add_u32 s27, s16, 0xa400000
	v_and_b32_e32 v132, -16, v132
	v_sub_u32_e32 v2, v2, v134
	s_addc_u32 s34, s17, 0
	v_add_u32_e32 v132, v140, v132
	v_ashrrev_i16_sdwa v2, v195, sext(v2) dst_sel:DWORD dst_unused:UNUSED_PAD src0_sel:DWORD src1_sel:BYTE_0
	s_add_u32 s35, s11, 0x900000
	v_lshlrev_b32_e32 v135, 5, v139
	v_bfe_i32 v141, v2, 0, 16
	v_lshlrev_b32_e32 v2, 1, v132
	v_lshrrev_b32_e32 v134, 2, v132
	v_and_b32_e32 v136, 3, v140
	s_mov_b32 s11, 0x1fffe0
	v_and_b32_e32 v135, 32, v135
	v_and_b32_e32 v2, 24, v2
	v_and_b32_e32 v134, 4, v134
	v_and_or_b32 v136, v132, s11, v136
	v_or3_b32 v2, v136, v134, v2
	v_add_lshl_u32 v134, v135, v141, 1
	v_add_u32_e32 v133, 0x2000, v133
	v_lshl_add_u32 v132, v132, 11, v134
	v_lshl_add_u32 v2, v2, 11, v134
	v_ashrrev_i32_e32 v134, 31, v133
	v_lshrrev_b32_e32 v134, 22, v134
	v_add_u32_e32 v134, v133, v134
	v_ashrrev_i32_e32 v142, 10, v134
	v_mul_i32_i24_e32 v134, 0x400, v142
	v_sub_u32_e32 v133, v133, v134
	v_lshrrev_b32_e32 v134, 4, v133
	v_bitop3_b32 v133, v134, v133, 32 bitop3:0x6c
	v_ashrrev_i32_e32 v135, 31, v133
	v_lshrrev_b32_e32 v135, 26, v135
	v_mov_b32_e32 v156, s6
	v_add_u32_e32 v135, v133, v135
	v_readfirstlane_b32 s24, v156
	s_addc_u32 s54, s12, 0
	v_lshlrev_b32_e32 v134, 3, v142
	v_ashrrev_i32_e32 v143, 6, v135
	v_and_b32_e32 v135, 0xc0, v135
	s_lshl_b32 s55, s3, 10
	s_ashr_i32 s3, s2, 31
	s_bfe_i64 s[14:15], s[24:25], 0x80000
	v_and_b32_e32 v134, -16, v134
	v_sub_u32_e32 v133, v133, v135
	s_lshl_b64 s[12:13], s[2:3], 19
	s_lshl_b64 s[14:15], s[14:15], 19
	v_add_u32_e32 v134, v143, v134
	v_ashrrev_i16_sdwa v133, v195, sext(v133) dst_sel:DWORD dst_unused:UNUSED_PAD src0_sel:DWORD src1_sel:BYTE_0
	s_add_u32 s70, s35, s14
	v_lshlrev_b32_e32 v136, 5, v142
	v_bfe_i32 v144, v133, 0, 16
	v_lshlrev_b32_e32 v133, 1, v134
	v_lshrrev_b32_e32 v135, 2, v134
	v_and_b32_e32 v137, 3, v143
	s_addc_u32 s71, s54, s15
	s_add_i32 s3, s55, 0
	v_and_b32_e32 v136, 32, v136
	v_and_b32_e32 v133, 24, v133
	v_and_b32_e32 v135, 4, v135
	v_and_or_b32 v137, v134, s11, v137
	s_waitcnt lgkmcnt(0)
	s_barrier
	s_add_i32 m0, s3, 0x10000
	v_or3_b32 v133, v137, v135, v133
	v_add_lshl_u32 v135, v136, v144, 1
	global_load_lds_dwordx4 v2, s[70:71]
	s_add_i32 m0, s3, 0x12000
	v_lshl_add_u32 v136, v133, 11, v135
	s_add_u32 s14, s70, 0x40000
	global_load_lds_dwordx4 v136, s[70:71]
	s_addc_u32 s15, s71, 0
	s_add_i32 m0, s3, 0x14000
	v_lshl_add_u32 v134, v134, 11, v135
	global_load_lds_dwordx4 v2, s[14:15]
	s_add_i32 m0, s3, 0x16000
	s_add_u32 s64, s27, s12
	s_addc_u32 s65, s34, s13
	s_add_i32 s24, s3, 0x2000
	global_load_lds_dwordx4 v136, s[14:15]
	s_mov_b32 m0, s3
	s_add_u32 s12, s64, 0x40000
	global_load_lds_dwordx4 v132, s[64:65]
	s_mov_b32 m0, s24
	s_addc_u32 s13, s65, 0
	s_add_i32 s56, s3, 0x4000
	global_load_lds_dwordx4 v134, s[64:65]
	s_mov_b32 m0, s56
	s_add_i32 s57, s3, 0x6000
	global_load_lds_dwordx4 v132, s[12:13]
	s_mov_b32 m0, s57
	s_waitcnt vmcnt(7)
	v_lshlrev_b32_e32 v128, 16, v64
	global_load_lds_dwordx4 v134, s[12:13]
	v_and_b32_e32 v129, 0xffff0000, v64
	v_lshlrev_b32_e32 v130, 16, v65
	v_and_b32_e32 v131, 0xffff0000, v65
	v_lshlrev_b32_e32 v124, 16, v66
	v_and_b32_e32 v125, 0xffff0000, v66
	v_lshlrev_b32_e32 v126, 16, v67
	v_and_b32_e32 v127, 0xffff0000, v67
	v_lshlrev_b32_e32 v116, 16, v56
	v_and_b32_e32 v117, 0xffff0000, v56
	v_lshlrev_b32_e32 v118, 16, v57
	v_and_b32_e32 v119, 0xffff0000, v57
	v_lshlrev_b32_e32 v120, 16, v58
	v_and_b32_e32 v121, 0xffff0000, v58
	v_lshlrev_b32_e32 v122, 16, v59
	v_and_b32_e32 v123, 0xffff0000, v59
	v_lshlrev_b32_e32 v112, 16, v60
	v_and_b32_e32 v113, 0xffff0000, v60
	v_lshlrev_b32_e32 v114, 16, v61
	v_and_b32_e32 v115, 0xffff0000, v61
	v_lshlrev_b32_e32 v108, 16, v62
	v_and_b32_e32 v109, 0xffff0000, v62
	v_lshlrev_b32_e32 v110, 16, v63
	v_and_b32_e32 v111, 0xffff0000, v63
	v_lshlrev_b32_e32 v100, 16, v48
	v_and_b32_e32 v101, 0xffff0000, v48
	v_lshlrev_b32_e32 v102, 16, v49
	v_and_b32_e32 v103, 0xffff0000, v49
	v_lshlrev_b32_e32 v104, 16, v50
	v_and_b32_e32 v105, 0xffff0000, v50
	v_lshlrev_b32_e32 v106, 16, v51
	v_and_b32_e32 v107, 0xffff0000, v51
	v_lshlrev_b32_e32 v88, 16, v52
	v_and_b32_e32 v89, 0xffff0000, v52
	v_lshlrev_b32_e32 v90, 16, v53
	v_and_b32_e32 v91, 0xffff0000, v53
	v_lshlrev_b32_e32 v96, 16, v54
	v_and_b32_e32 v97, 0xffff0000, v54
	v_lshlrev_b32_e32 v98, 16, v55
	v_and_b32_e32 v99, 0xffff0000, v55
	v_lshlrev_b32_e32 v84, 16, v40
	v_and_b32_e32 v85, 0xffff0000, v40
	v_lshlrev_b32_e32 v86, 16, v41
	v_and_b32_e32 v87, 0xffff0000, v41
	v_lshlrev_b32_e32 v92, 16, v42
	v_and_b32_e32 v93, 0xffff0000, v42
	v_lshlrev_b32_e32 v94, 16, v43
	v_and_b32_e32 v95, 0xffff0000, v43
	v_lshlrev_b32_e32 v80, 16, v44
	v_and_b32_e32 v81, 0xffff0000, v44
	v_lshlrev_b32_e32 v82, 16, v45
	v_and_b32_e32 v83, 0xffff0000, v45
	v_lshlrev_b32_e32 v76, 16, v46
	v_and_b32_e32 v77, 0xffff0000, v46
	v_lshlrev_b32_e32 v78, 16, v47
	v_and_b32_e32 v79, 0xffff0000, v47
	v_lshlrev_b32_e32 v68, 16, v32
	v_and_b32_e32 v69, 0xffff0000, v32
	v_lshlrev_b32_e32 v70, 16, v33
	v_and_b32_e32 v71, 0xffff0000, v33
	v_lshlrev_b32_e32 v72, 16, v34
	v_and_b32_e32 v73, 0xffff0000, v34
	v_lshlrev_b32_e32 v74, 16, v35
	v_and_b32_e32 v75, 0xffff0000, v35
	v_lshlrev_b32_e32 v64, 16, v36
	v_and_b32_e32 v65, 0xffff0000, v36
	v_lshlrev_b32_e32 v66, 16, v37
	v_and_b32_e32 v67, 0xffff0000, v37
	v_lshlrev_b32_e32 v60, 16, v38
	v_and_b32_e32 v61, 0xffff0000, v38
	v_lshlrev_b32_e32 v62, 16, v39
	v_and_b32_e32 v63, 0xffff0000, v39
	v_lshlrev_b32_e32 v52, 16, v24
	v_and_b32_e32 v53, 0xffff0000, v24
	v_lshlrev_b32_e32 v54, 16, v25
	v_and_b32_e32 v55, 0xffff0000, v25
	v_lshlrev_b32_e32 v56, 16, v26
	v_and_b32_e32 v57, 0xffff0000, v26
	v_lshlrev_b32_e32 v58, 16, v27
	v_and_b32_e32 v59, 0xffff0000, v27
	v_lshlrev_b32_e32 v48, 16, v28
	v_and_b32_e32 v49, 0xffff0000, v28
	v_lshlrev_b32_e32 v50, 16, v29
	v_and_b32_e32 v51, 0xffff0000, v29
	v_lshlrev_b32_e32 v44, 16, v30
	v_and_b32_e32 v45, 0xffff0000, v30
	v_lshlrev_b32_e32 v46, 16, v31
	v_and_b32_e32 v47, 0xffff0000, v31
	v_lshlrev_b32_e32 v36, 16, v16
	v_and_b32_e32 v37, 0xffff0000, v16
	v_lshlrev_b32_e32 v38, 16, v17
	v_and_b32_e32 v39, 0xffff0000, v17
	v_lshlrev_b32_e32 v40, 16, v18
	v_and_b32_e32 v41, 0xffff0000, v18
	v_lshlrev_b32_e32 v42, 16, v19
	v_and_b32_e32 v43, 0xffff0000, v19
	v_lshlrev_b32_e32 v32, 16, v20
	v_and_b32_e32 v33, 0xffff0000, v20
	v_lshlrev_b32_e32 v34, 16, v21
	v_and_b32_e32 v35, 0xffff0000, v21
	v_lshlrev_b32_e32 v28, 16, v22
	v_and_b32_e32 v29, 0xffff0000, v22
	v_lshlrev_b32_e32 v30, 16, v23
	v_and_b32_e32 v31, 0xffff0000, v23
	v_lshlrev_b32_e32 v20, 16, v4
	v_and_b32_e32 v21, 0xffff0000, v4
	v_lshlrev_b32_e32 v22, 16, v5
	v_and_b32_e32 v23, 0xffff0000, v5
	v_lshlrev_b32_e32 v24, 16, v6
	v_and_b32_e32 v25, 0xffff0000, v6
	v_lshlrev_b32_e32 v26, 16, v7
	v_and_b32_e32 v27, 0xffff0000, v7
	v_lshlrev_b32_e32 v16, 16, v12
	v_and_b32_e32 v17, 0xffff0000, v12
	v_lshlrev_b32_e32 v18, 16, v13
	v_and_b32_e32 v19, 0xffff0000, v13
	v_lshlrev_b32_e32 v12, 16, v14
	v_and_b32_e32 v13, 0xffff0000, v14
	v_lshlrev_b32_e32 v14, 16, v15
	v_and_b32_e32 v15, 0xffff0000, v15
	v_lshlrev_b32_e32 v4, 16, v8
	v_and_b32_e32 v5, 0xffff0000, v8
	v_lshlrev_b32_e32 v6, 16, v9
	v_and_b32_e32 v7, 0xffff0000, v9
	v_lshlrev_b32_e32 v8, 16, v10
	v_and_b32_e32 v9, 0xffff0000, v10
	v_lshlrev_b32_e32 v10, 16, v11
	v_and_b32_e32 v11, 0xffff0000, v11
	s_cmp_lg_u32 s10, 1
	s_cbranch_scc1 .LBB0_595
	s_barrier

.LBB0_823:
	s_or_b64 exec, exec, s[62:63]
	v_ashrrev_i32_e32 v2, 31, v153
	v_lshrrev_b32_e32 v2, 26, v2
	v_add_u32_e32 v2, v153, v2
	v_ashrrev_i32_e32 v139, 6, v2
	v_bfe_i32 v2, v153, 27, 1
	v_lshlrev_b32_e32 v133, 4, v153
	v_lshrrev_b32_e32 v2, 22, v2
	v_add_u32_e32 v2, v133, v2
	v_and_b32_e32 v2, 0xfffffc00, v2
	v_sub_u32_e32 v2, v133, v2
	v_lshrrev_b32_e32 v132, 4, v2
	v_bitop3_b32 v2, v132, v2, 32 bitop3:0x6c
	v_ashrrev_i32_e32 v134, 31, v2
	s_lshr_b32 s11, s11, 3
	v_lshrrev_b32_e32 v134, 26, v134
	s_add_u32 s12, s18, s94
	v_add_u32_e32 v134, v2, v134
	s_addc_u32 s13, s19, 0
	v_lshlrev_b32_e32 v132, 3, v139
	v_ashrrev_i32_e32 v140, 6, v134
	v_and_b32_e32 v134, 0xc0, v134
	s_add_u32 s27, s18, 0x5400000
	v_and_b32_e32 v132, -16, v132
	v_sub_u32_e32 v2, v2, v134
	s_addc_u32 s34, s19, 0
	v_add_u32_e32 v132, v140, v132
	v_ashrrev_i16_sdwa v2, v195, sext(v2) dst_sel:DWORD dst_unused:UNUSED_PAD src0_sel:DWORD src1_sel:BYTE_0
	s_add_u32 s35, s12, 0x1600000
	v_lshlrev_b32_e32 v135, 5, v139
	v_bfe_i32 v141, v2, 0, 16
	v_lshlrev_b32_e32 v2, 1, v132
	v_lshrrev_b32_e32 v134, 2, v132
	v_and_b32_e32 v136, 3, v140
	s_mov_b32 s12, 0x1ffffe0
	v_and_b32_e32 v135, 32, v135
	v_and_b32_e32 v2, 24, v2
	v_and_b32_e32 v134, 4, v134
	v_and_or_b32 v136, v132, s12, v136
	v_or3_b32 v2, v136, v134, v2
	v_add_lshl_u32 v134, v135, v141, 1
	v_add_u32_e32 v133, 0x2000, v133
	v_lshl_add_u32 v132, v132, 7, v134
	v_lshl_add_u32 v2, v2, 7, v134
	v_ashrrev_i32_e32 v134, 31, v133
	v_lshrrev_b32_e32 v134, 22, v134
	v_add_u32_e32 v134, v133, v134
	v_ashrrev_i32_e32 v142, 10, v134
	v_mul_i32_i24_e32 v134, 0x400, v142
	v_sub_u32_e32 v133, v133, v134
	v_lshrrev_b32_e32 v134, 4, v133
	v_bitop3_b32 v133, v134, v133, 32 bitop3:0x6c
	v_ashrrev_i32_e32 v135, 31, v133
	v_lshrrev_b32_e32 v135, 26, v135
	v_lshlrev_b32_e32 v134, 3, v142
	v_add_u32_e32 v135, v133, v135
	v_mov_b32_e32 v156, s11
	v_and_b32_e32 v134, -16, v134
	v_ashrrev_i32_e32 v143, 6, v135
	v_readfirstlane_b32 s24, v156
	s_addc_u32 s54, s13, 0
	v_add_u32_e32 v134, v143, v134
	v_and_b32_e32 v135, 0xc0, v135
	v_and_b32_e32 v137, 3, v143
	s_ashr_i32 s61, s60, 31
	s_bfe_i64 s[14:15], s[24:25], 0x80000
	v_sub_u32_e32 v133, v133, v135
	v_and_or_b32 v137, v134, s12, v137
	s_lshl_b32 s55, s6, 10
	s_lshl_b64 s[12:13], s[60:61], 15
	s_lshl_b64 s[14:15], s[14:15], 15
	v_ashrrev_i16_sdwa v133, v195, sext(v133) dst_sel:DWORD dst_unused:UNUSED_PAD src0_sel:DWORD src1_sel:BYTE_0
	s_add_u32 s66, s35, s14
	v_lshlrev_b32_e32 v136, 5, v142
	v_bfe_i32 v144, v133, 0, 16
	v_lshlrev_b32_e32 v133, 1, v134
	v_lshrrev_b32_e32 v135, 2, v134
	s_addc_u32 s67, s54, s15
	s_add_i32 s24, s55, 0
	v_and_b32_e32 v136, 32, v136
	v_and_b32_e32 v133, 24, v133
	v_and_b32_e32 v135, 4, v135
	s_waitcnt lgkmcnt(0)
	s_barrier
	s_add_i32 m0, s24, 0x10000
	v_or3_b32 v133, v137, v135, v133
	v_add_lshl_u32 v135, v136, v144, 1
	global_load_lds_dwordx4 v2, s[66:67]
	s_add_i32 m0, s24, 0x12000
	v_lshl_add_u32 v136, v133, 7, v135
	s_add_u32 s14, s66, 0x4000
	global_load_lds_dwordx4 v136, s[66:67]
	s_addc_u32 s15, s67, 0
	s_add_i32 m0, s24, 0x14000
	v_lshl_add_u32 v134, v134, 7, v135
	global_load_lds_dwordx4 v2, s[14:15]
	s_add_i32 m0, s24, 0x16000
	s_add_u32 s68, s27, s12
	s_addc_u32 s69, s34, s13
	s_add_i32 s56, s24, 0x2000
	global_load_lds_dwordx4 v136, s[14:15]
	s_mov_b32 m0, s24
	s_add_u32 s12, s68, 0x4000
	global_load_lds_dwordx4 v132, s[68:69]
	s_mov_b32 m0, s56
	s_addc_u32 s13, s69, 0
	s_add_i32 s57, s24, 0x4000
	global_load_lds_dwordx4 v134, s[68:69]
	s_mov_b32 m0, s57
	s_add_i32 s59, s24, 0x6000
	global_load_lds_dwordx4 v132, s[12:13]
	s_mov_b32 m0, s59
	s_waitcnt vmcnt(7)
	v_lshlrev_b32_e32 v128, 16, v72
	global_load_lds_dwordx4 v134, s[12:13]
	v_and_b32_e32 v129, 0xffff0000, v72
	v_lshlrev_b32_e32 v130, 16, v73
	v_and_b32_e32 v131, 0xffff0000, v73
	v_lshlrev_b32_e32 v124, 16, v74
	v_and_b32_e32 v125, 0xffff0000, v74
	v_lshlrev_b32_e32 v126, 16, v75
	v_and_b32_e32 v127, 0xffff0000, v75
	v_lshlrev_b32_e32 v120, 16, v64
	v_and_b32_e32 v121, 0xffff0000, v64
	v_lshlrev_b32_e32 v122, 16, v65
	v_and_b32_e32 v123, 0xffff0000, v65
	v_lshlrev_b32_e32 v116, 16, v66
	v_and_b32_e32 v117, 0xffff0000, v66
	v_lshlrev_b32_e32 v118, 16, v67
	v_and_b32_e32 v119, 0xffff0000, v67
	v_lshlrev_b32_e32 v104, 16, v68
	v_and_b32_e32 v105, 0xffff0000, v68
	v_lshlrev_b32_e32 v106, 16, v69
	v_and_b32_e32 v107, 0xffff0000, v69
	v_lshlrev_b32_e32 v100, 16, v70
	v_and_b32_e32 v101, 0xffff0000, v70
	v_lshlrev_b32_e32 v102, 16, v71
	v_and_b32_e32 v103, 0xffff0000, v71
	v_lshlrev_b32_e32 v112, 16, v56
	v_and_b32_e32 v113, 0xffff0000, v56
	v_lshlrev_b32_e32 v114, 16, v57
	v_and_b32_e32 v115, 0xffff0000, v57
	v_lshlrev_b32_e32 v108, 16, v58
	v_and_b32_e32 v109, 0xffff0000, v58
	v_lshlrev_b32_e32 v110, 16, v59
	v_and_b32_e32 v111, 0xffff0000, v59
	v_lshlrev_b32_e32 v84, 16, v60
	v_and_b32_e32 v85, 0xffff0000, v60
	v_lshlrev_b32_e32 v86, 16, v61
	v_and_b32_e32 v87, 0xffff0000, v61
	v_lshlrev_b32_e32 v88, 16, v62
	v_and_b32_e32 v89, 0xffff0000, v62
	v_lshlrev_b32_e32 v90, 16, v63
	v_and_b32_e32 v91, 0xffff0000, v63
	v_lshlrev_b32_e32 v92, 16, v48
	v_and_b32_e32 v93, 0xffff0000, v48
	v_lshlrev_b32_e32 v94, 16, v49
	v_and_b32_e32 v95, 0xffff0000, v49
	v_lshlrev_b32_e32 v96, 16, v50
	v_and_b32_e32 v97, 0xffff0000, v50
	v_lshlrev_b32_e32 v98, 16, v51
	v_and_b32_e32 v99, 0xffff0000, v51
	v_lshlrev_b32_e32 v72, 16, v52
	v_and_b32_e32 v73, 0xffff0000, v52
	v_lshlrev_b32_e32 v74, 16, v53
	v_and_b32_e32 v75, 0xffff0000, v53
	v_lshlrev_b32_e32 v68, 16, v54
	v_and_b32_e32 v69, 0xffff0000, v54
	v_lshlrev_b32_e32 v70, 16, v55
	v_and_b32_e32 v71, 0xffff0000, v55
	v_lshlrev_b32_e32 v80, 16, v40
	v_and_b32_e32 v81, 0xffff0000, v40
	v_lshlrev_b32_e32 v82, 16, v41
	v_and_b32_e32 v83, 0xffff0000, v41
	v_lshlrev_b32_e32 v76, 16, v42
	v_and_b32_e32 v77, 0xffff0000, v42
	v_lshlrev_b32_e32 v78, 16, v43
	v_and_b32_e32 v79, 0xffff0000, v43
	v_lshlrev_b32_e32 v56, 16, v44
	v_and_b32_e32 v57, 0xffff0000, v44
	v_lshlrev_b32_e32 v58, 16, v45
	v_and_b32_e32 v59, 0xffff0000, v45
	v_lshlrev_b32_e32 v52, 16, v46
	v_and_b32_e32 v53, 0xffff0000, v46
	v_lshlrev_b32_e32 v54, 16, v47
	v_and_b32_e32 v55, 0xffff0000, v47
	v_lshlrev_b32_e32 v64, 16, v30
	v_and_b32_e32 v65, 0xffff0000, v30
	v_lshlrev_b32_e32 v66, 16, v31
	v_and_b32_e32 v67, 0xffff0000, v31
	v_lshlrev_b32_e32 v60, 16, v32
	v_and_b32_e32 v61, 0xffff0000, v32
	v_lshlrev_b32_e32 v62, 16, v33
	v_and_b32_e32 v63, 0xffff0000, v33
	v_lshlrev_b32_e32 v40, 16, v36
	v_and_b32_e32 v41, 0xffff0000, v36
	v_lshlrev_b32_e32 v42, 16, v37
	v_and_b32_e32 v43, 0xffff0000, v37
	v_lshlrev_b32_e32 v36, 16, v38
	v_and_b32_e32 v37, 0xffff0000, v38
	v_lshlrev_b32_e32 v38, 16, v39
	v_and_b32_e32 v39, 0xffff0000, v39
	v_lshlrev_b32_e32 v48, 16, v20
	v_and_b32_e32 v49, 0xffff0000, v20
	v_lshlrev_b32_e32 v50, 16, v21
	v_and_b32_e32 v51, 0xffff0000, v21
	v_lshlrev_b32_e32 v44, 16, v22
	v_and_b32_e32 v45, 0xffff0000, v22
	v_lshlrev_b32_e32 v46, 16, v23
	v_and_b32_e32 v47, 0xffff0000, v23
	v_lshlrev_b32_e32 v24, 16, v26
	v_and_b32_e32 v25, 0xffff0000, v26
	v_lshlrev_b32_e32 v26, 16, v27
	v_and_b32_e32 v27, 0xffff0000, v27
	v_lshlrev_b32_e32 v20, 16, v28
	v_and_b32_e32 v21, 0xffff0000, v28
	v_lshlrev_b32_e32 v22, 16, v29
	v_and_b32_e32 v23, 0xffff0000, v29
	v_lshlrev_b32_e32 v32, 16, v4
	v_and_b32_e32 v33, 0xffff0000, v4
	v_lshlrev_b32_e32 v34, 16, v5
	v_and_b32_e32 v35, 0xffff0000, v5
	v_lshlrev_b32_e32 v28, 16, v6
	v_and_b32_e32 v29, 0xffff0000, v6
	v_lshlrev_b32_e32 v30, 16, v7
	v_and_b32_e32 v31, 0xffff0000, v7
	v_lshlrev_b32_e32 v8, 16, v10
	v_and_b32_e32 v9, 0xffff0000, v10
	v_lshlrev_b32_e32 v10, 16, v11
	v_and_b32_e32 v11, 0xffff0000, v11
	v_lshlrev_b32_e32 v4, 16, v12
	v_and_b32_e32 v5, 0xffff0000, v12
	v_lshlrev_b32_e32 v6, 16, v13
	v_and_b32_e32 v7, 0xffff0000, v13
	v_lshlrev_b32_e32 v12, 16, v16
	v_and_b32_e32 v13, 0xffff0000, v16
	v_lshlrev_b32_e32 v14, 16, v17
	v_and_b32_e32 v15, 0xffff0000, v17
	v_lshlrev_b32_e32 v16, 16, v18
	v_and_b32_e32 v17, 0xffff0000, v18
	v_lshlrev_b32_e32 v18, 16, v19
	v_and_b32_e32 v19, 0xffff0000, v19
	s_cmp_lg_u32 s10, 1
	s_cbranch_scc1 .LBB0_825
	s_barrier
